# attention unit prologue: the 12 query-gain vector loads issued together (one wait) instead of 6 load-pair round trips
# baseline (speedup 1.0000x reference)
; #define LAS __attribute__((address_space(3)))
; DEV void attn_unit(int b, int h, int qb, const bf16_t* Q, const bf16_t* K, const bf16_t* V, bf16_t* O, LAS unsigned char* sh, const int tid, const float* qgain) {
;     const int lane = tid & 63, r32 = lane & 31, hi = lane >> 5; const int wid = __builtin_amdgcn_readfirstlane(tid >> 6);
;     const long qrow0 = (long)b * SEQ + qb * 256 + wid * 32;
;     const bf16_t* Qw = Q + qrow0 * 1536 + h * 96;
;     const unsigned lds0 = (unsigned)(uintptr_t)sh;
;     LAS float* wsf = (LAS float*)(sh + OFF_WS) + wid * 64;
;     bf16x8 qr[6];
; #pragma unroll
;     for (int d0 = 0; d0 < 6; ++d0) qr[d0] = *(const bf16x8*)(Qw + (long)r32 * 1536 + d0 * 16 + hi * 8);
;     {
;         float qv[6][8]; float ss = 0.f;
; #pragma unroll
;         for (int d0 = 0; d0 < 6; ++d0) { const u32x4 raw = __builtin_bit_cast(u32x4, qr[d0]);
;             qv[d0][0] = __uint_as_float(raw.x << 16); qv[d0][1] = __uint_as_float(raw.x & 0xffff0000u); qv[d0][2] = __uint_as_float(raw.y << 16); qv[d0][3] = __uint_as_float(raw.y & 0xffff0000u);
;             qv[d0][4] = __uint_as_float(raw.z << 16); qv[d0][5] = __uint_as_float(raw.z & 0xffff0000u); qv[d0][6] = __uint_as_float(raw.w << 16); qv[d0][7] = __uint_as_float(raw.w & 0xffff0000u);
; #pragma unroll
;             for (int e = 0; e < 8; ++e) ss += qv[d0][e] * qv[d0][e]; }
;         ss += __shfl_xor(ss, 32);
.LBB0_2104:
	s_lshl_b32 s4, s31, 5
	s_add_i32 s7, s30, s4
	v_readlane_b32 s4, v248, 2
	s_add_i32 s6, s31, s1
	v_readlane_b32 s5, v248, 3
	s_and_b64 s[4:5], s[4:5], exec
	s_cselect_b32 s18, s7, s6
	s_cmpk_gt_i32 s18, 0x7ff
	s_mov_b64 s[4:5], -1
	s_cbranch_scc1 .LBB0_2103
	s_ashr_i32 s4, s18, 8
	v_readfirstlane_b32 s19, v135
	s_ashr_i32 s5, s4, 31
	s_ashr_i32 s21, s19, 6
	s_lshl_b64 s[8:9], s[4:5], 12
	s_lshl_b32 s4, s18, 8
	v_readlane_b32 s6, v251, 31
	s_and_b32 s15, s4, 0xf00
	s_lshl_b32 s14, s21, 5
	s_bfe_u32 s20, s18, 0x40004
	v_readlane_b32 s7, v251, 32
	s_or_b32 s4, s8, s15
	s_ashr_i32 s5, s14, 31
	s_load_dwordx2 s[12:13], s[6:7], 0xf0
	s_add_u32 s6, s4, s14
	s_addc_u32 s7, s9, s5
	s_mul_i32 s4, s7, 0xc00
	s_mul_hi_u32 s5, s6, 0xc00
	s_add_i32 s5, s5, s4
	s_mul_i32 s4, s6, 0xc00
	v_readlane_b32 s10, v251, 54
	v_readlane_b32 s11, v251, 55
	s_add_u32 s4, s10, s4
	s_mul_i32 s10, s20, 0x60
	s_addc_u32 s5, s11, s5
	s_lshl_b32 s10, s10, 1
	s_add_u32 s4, s4, s10
	s_addc_u32 s5, s5, 0
	v_mov_b32_e32 v141, v97
	v_lshl_add_u64 v[0:1], s[4:5], 0, v[140:141]
	v_lshlrev_b32_e32 v96, 1, v134
	v_lshl_add_u64 v[16:17], v[0:1], 0, v[96:97]
	global_load_dwordx4 v[0:3], v[16:17], off
	global_load_dwordx4 v[4:7], v[16:17], off offset:32
	global_load_dwordx4 v[8:11], v[16:17], off offset:64
	global_load_dwordx4 v[12:15], v[16:17], off offset:96
	global_load_dwordx4 v[50:53], v[16:17], off offset:128
	global_load_dwordx4 v[54:57], v[16:17], off offset:160
	v_xor_b32_e32 v40, 32, v183
	s_mov_b32 s11, s88
	s_waitcnt vmcnt(5)
	v_and_b32_e32 v17, 0xffff0000, v0
	v_lshlrev_b32_e32 v16, 16, v0
	v_mul_f32_e32 v18, v17, v17
	v_lshlrev_b32_e32 v19, 16, v1
	v_fmac_f32_e32 v18, v16, v16
	v_and_b32_e32 v21, 0xffff0000, v1
	v_fmac_f32_e32 v18, v19, v19
	v_lshlrev_b32_e32 v20, 16, v2
	v_fmac_f32_e32 v18, v21, v21
	v_and_b32_e32 v22, 0xffff0000, v2
	v_fmac_f32_e32 v18, v20, v20
	v_lshlrev_b32_e32 v23, 16, v3
	v_fmac_f32_e32 v18, v22, v22
	v_and_b32_e32 v26, 0xffff0000, v3
	v_fmac_f32_e32 v18, v23, v23
	v_fmac_f32_e32 v18, v26, v26
	s_waitcnt vmcnt(4)
	v_lshlrev_b32_e32 v24, 16, v4
	v_and_b32_e32 v25, 0xffff0000, v4
	v_fmac_f32_e32 v18, v24, v24
	v_lshlrev_b32_e32 v27, 16, v5
	v_fmac_f32_e32 v18, v25, v25
	v_and_b32_e32 v29, 0xffff0000, v5
	v_fmac_f32_e32 v18, v27, v27
	v_lshlrev_b32_e32 v28, 16, v6
	v_fmac_f32_e32 v18, v29, v29
	v_and_b32_e32 v30, 0xffff0000, v6
	v_fmac_f32_e32 v18, v28, v28
	v_lshlrev_b32_e32 v31, 16, v7
	v_fmac_f32_e32 v18, v30, v30
	v_and_b32_e32 v34, 0xffff0000, v7
	v_fmac_f32_e32 v18, v31, v31
	v_fmac_f32_e32 v18, v34, v34
	s_waitcnt vmcnt(3)
	v_lshlrev_b32_e32 v32, 16, v8
	v_and_b32_e32 v33, 0xffff0000, v8
	v_fmac_f32_e32 v18, v32, v32
	v_lshlrev_b32_e32 v35, 16, v9
	v_fmac_f32_e32 v18, v33, v33
	v_and_b32_e32 v37, 0xffff0000, v9
	v_fmac_f32_e32 v18, v35, v35
	v_lshlrev_b32_e32 v36, 16, v10
	v_fmac_f32_e32 v18, v37, v37
	v_and_b32_e32 v38, 0xffff0000, v10
	v_fmac_f32_e32 v18, v36, v36
	v_lshlrev_b32_e32 v39, 16, v11
	v_fmac_f32_e32 v18, v38, v38
	v_and_b32_e32 v49, 0xffff0000, v11
	v_fmac_f32_e32 v18, v39, v39
	v_fmac_f32_e32 v18, v49, v49
	s_waitcnt vmcnt(2)
	v_lshlrev_b32_e32 v47, 16, v12
	v_and_b32_e32 v45, 0xffff0000, v12
	v_fmac_f32_e32 v18, v47, v47
	v_lshlrev_b32_e32 v43, 16, v13
	v_fmac_f32_e32 v18, v45, v45
	v_and_b32_e32 v41, 0xffff0000, v13
	v_fmac_f32_e32 v18, v43, v43
	v_lshlrev_b32_e32 v48, 16, v14
	v_fmac_f32_e32 v18, v41, v41
	v_and_b32_e32 v46, 0xffff0000, v14
	v_fmac_f32_e32 v18, v48, v48
	v_lshlrev_b32_e32 v44, 16, v15
	v_fmac_f32_e32 v18, v46, v46
	v_and_b32_e32 v42, 0xffff0000, v15
	v_fmac_f32_e32 v18, v44, v44
	v_fmac_f32_e32 v18, v42, v42
	s_waitcnt vmcnt(1)
	v_lshlrev_b32_e32 v6, 16, v50
	v_and_b32_e32 v4, 0xffff0000, v50
	v_fmac_f32_e32 v18, v6, v6
	v_lshlrev_b32_e32 v2, 16, v51
	v_fmac_f32_e32 v18, v4, v4
	v_and_b32_e32 v0, 0xffff0000, v51
	v_fmac_f32_e32 v18, v2, v2
	v_lshlrev_b32_e32 v7, 16, v52
	v_fmac_f32_e32 v18, v0, v0
	v_and_b32_e32 v5, 0xffff0000, v52
	v_fmac_f32_e32 v18, v7, v7
	v_lshlrev_b32_e32 v3, 16, v53
	v_fmac_f32_e32 v18, v5, v5
	v_and_b32_e32 v1, 0xffff0000, v53
	v_fmac_f32_e32 v18, v3, v3
	v_fmac_f32_e32 v18, v1, v1
	s_waitcnt vmcnt(0)
	v_lshlrev_b32_e32 v14, 16, v54
	v_and_b32_e32 v12, 0xffff0000, v54
	v_fmac_f32_e32 v18, v14, v14
	v_lshlrev_b32_e32 v11, 16, v55
	v_fmac_f32_e32 v18, v12, v12
	v_and_b32_e32 v10, 0xffff0000, v55
	v_fmac_f32_e32 v18, v11, v11
	v_lshlrev_b32_e32 v15, 16, v56
	v_fmac_f32_e32 v18, v10, v10
	v_and_b32_e32 v13, 0xffff0000, v56
	v_fmac_f32_e32 v18, v15, v15
	v_and_b32_e32 v8, 0xffff0000, v57
	v_lshlrev_b32_e32 v9, 16, v57
	v_fmac_f32_e32 v18, v13, v13
	v_pk_mul_f32 v[50:51], v[8:9], v[8:9]
	s_nop 0
	v_add_f32_e32 v18, v51, v18
	v_add_f32_e32 v18, v50, v18
	v_and_b32_e32 v50, 64, v183
	v_add_u32_e32 v50, 64, v50
	v_cmp_lt_i32_e32 vcc, v40, v50
	s_nop 1
	v_cndmask_b32_e32 v40, v183, v40, vcc
	v_lshlrev_b32_e32 v141, 2, v40
	ds_bpermute_b32 v40, v141, v18
	s_waitcnt lgkmcnt(0)
; DEV void attn_unit(int b, int h, int qb, const bf16_t* Q, const bf16_t* K, const bf16_t* V, bf16_t* O, LAS unsigned char* sh, const int tid, const float* qgain) {
;     ...
;         const float rstd = 1.0f / sqrtf(ss * (1.f / 96.f) + EPS);
; #pragma unroll
;         for (int d0 = 0; d0 < 6; ++d0) { const f32x4 g0 = *(const f32x4*)(qgain + d0 * 16 + hi * 8), g1 = *(const f32x4*)(qgain + d0 * 16 + hi * 8 + 4);
; #pragma unroll
;             for (int e = 0; e < 4; ++e) { qv[d0][e] *= rstd * g0[e]; qv[d0][4 + e] *= rstd * g1[e]; } }
	v_lshlrev_b32_e32 v244, 2, v134
	global_load_dwordx4 v[196:199], v244, s[12:13] offset:16
	global_load_dwordx4 v[200:203], v244, s[12:13]
	global_load_dwordx4 v[204:207], v244, s[12:13] offset:80
	global_load_dwordx4 v[208:211], v244, s[12:13] offset:64
	global_load_dwordx4 v[212:215], v244, s[12:13] offset:144
	global_load_dwordx4 v[216:219], v244, s[12:13] offset:128
	global_load_dwordx4 v[220:223], v244, s[12:13] offset:208
	global_load_dwordx4 v[224:227], v244, s[12:13] offset:192
	global_load_dwordx4 v[228:231], v244, s[12:13] offset:272
	global_load_dwordx4 v[232:235], v244, s[12:13] offset:256
	global_load_dwordx4 v[236:239], v244, s[12:13] offset:336
	global_load_dwordx4 v[240:243], v244, s[12:13] offset:320
	v_add_f32_e32 v18, v18, v40
	v_fmamk_f32 v18, v18, 0x3c2aaaab, v180
	v_cmp_gt_f32_e32 vcc, s78, v18
	v_mul_f32_e32 v40, 0x4f800000, v18
	s_nop 0
	v_cndmask_b32_e32 v18, v18, v40, vcc
	v_sqrt_f32_e32 v40, v18
	s_nop 0
	v_add_u32_e32 v50, -1, v40
	v_fma_f32 v51, -v50, v40, v18
	v_cmp_ge_f32_e64 s[4:5], 0, v51
	v_add_u32_e32 v51, 1, v40
	s_nop 0
	v_cndmask_b32_e64 v50, v40, v50, s[4:5]
	v_fma_f32 v40, -v51, v40, v18
	v_cmp_lt_f32_e64 s[4:5], 0, v40
	s_nop 1
	v_cndmask_b32_e64 v40, v50, v51, s[4:5]
	v_mul_f32_e32 v50, 0x37800000, v40
	v_cndmask_b32_e32 v40, v40, v50, vcc
	v_cmp_class_f32_e32 vcc, v18, v181
	s_nop 1
	v_cndmask_b32_e32 v18, v40, v18, vcc
	v_div_scale_f32 v40, s[4:5], v18, v18, 1.0
	v_rcp_f32_e32 v50, v40
	s_add_i32 s4, s14, s15
	s_ashr_i32 s4, s4, 6
	s_cmp_lt_i32 s21, 4
	v_fma_f32 v51, -v40, v50, 1.0
	v_fmac_f32_e32 v50, v51, v50
	v_div_scale_f32 v51, vcc, 1.0, v18, 1.0
	v_mul_f32_e32 v52, v51, v50
	v_fma_f32 v53, -v40, v52, v51
	v_fmac_f32_e32 v52, v53, v50
	v_fma_f32 v40, -v40, v52, v51
	v_div_fmas_f32 v40, v40, v50, v52
	v_lshlrev_b32_e32 v50, 2, v134
	s_waitcnt vmcnt(0)
	v_mov_b32_e32 v52, v196
	v_mov_b32_e32 v53, v197
	v_mov_b32_e32 v54, v198
	v_mov_b32_e32 v55, v199
	v_mov_b32_e32 v56, v200
	v_mov_b32_e32 v57, v201
	v_mov_b32_e32 v58, v202
	v_mov_b32_e32 v59, v203
	v_div_fixup_f32 v40, v40, v18, 1.0
	s_cselect_b64 s[16:17], -1, 0
	s_waitcnt vmcnt(0)
	v_mul_f32_e32 v18, v56, v40
	v_mul_f32_e32 v18, v18, v16
	v_mul_f32_e32 v16, v52, v40
	v_mul_f32_e32 v16, v16, v20
	v_mul_f32_e32 v20, v57, v40
	v_mul_f32_e32 v20, v20, v17
	v_mul_f32_e32 v17, v53, v40
	v_mul_f32_e32 v17, v17, v22
	v_mul_f32_e32 v22, v58, v40
	v_mul_f32_e32 v22, v22, v19
	v_mul_f32_e32 v19, v54, v40
	v_mul_f32_e32 v19, v19, v23
	v_mul_f32_e32 v23, v59, v40
	v_mul_f32_e32 v23, v23, v21
	v_mul_f32_e32 v21, v55, v40
	v_mov_b32_e32 v52, v204
	v_mov_b32_e32 v53, v205
	v_mov_b32_e32 v54, v206
	v_mov_b32_e32 v55, v207
	v_mov_b32_e32 v56, v208
	v_mov_b32_e32 v57, v209
	v_mov_b32_e32 v58, v210
	v_mov_b32_e32 v59, v211
	v_mul_f32_e32 v21, v21, v26
	s_waitcnt vmcnt(0)
	v_mul_f32_e32 v26, v56, v40
	v_mul_f32_e32 v26, v26, v24
	v_mul_f32_e32 v24, v52, v40
	v_mul_f32_e32 v24, v24, v28
	v_mul_f32_e32 v28, v57, v40
	v_mul_f32_e32 v28, v28, v25
	v_mul_f32_e32 v25, v53, v40
	v_mul_f32_e32 v25, v25, v30
	v_mul_f32_e32 v30, v58, v40
	v_mul_f32_e32 v30, v30, v27
	v_mul_f32_e32 v27, v54, v40
	v_mul_f32_e32 v27, v27, v31
	v_mul_f32_e32 v31, v59, v40
	v_mul_f32_e32 v31, v31, v29
	v_mul_f32_e32 v29, v55, v40
	v_mov_b32_e32 v52, v212
	v_mov_b32_e32 v53, v213
	v_mov_b32_e32 v54, v214
	v_mov_b32_e32 v55, v215
	v_mov_b32_e32 v56, v216
	v_mov_b32_e32 v57, v217
	v_mov_b32_e32 v58, v218
	v_mov_b32_e32 v59, v219
	v_mul_f32_e32 v29, v29, v34
	s_waitcnt vmcnt(0)
	v_mul_f32_e32 v34, v56, v40
	v_mul_f32_e32 v34, v34, v32
	v_mul_f32_e32 v32, v52, v40
	v_mul_f32_e32 v32, v32, v36
	v_mul_f32_e32 v36, v57, v40
	v_mul_f32_e32 v36, v36, v33
	v_mul_f32_e32 v33, v53, v40
	v_mul_f32_e32 v33, v33, v38
	v_mul_f32_e32 v38, v58, v40
	v_mul_f32_e32 v38, v38, v35
	v_mul_f32_e32 v35, v54, v40
	v_mul_f32_e32 v35, v35, v39
	v_mul_f32_e32 v39, v59, v40
	v_mul_f32_e32 v39, v39, v37
	v_mul_f32_e32 v37, v55, v40
	v_mov_b32_e32 v52, v220
	v_mov_b32_e32 v53, v221
	v_mov_b32_e32 v54, v222
	v_mov_b32_e32 v55, v223
	v_mov_b32_e32 v56, v224
	v_mov_b32_e32 v57, v225
	v_mov_b32_e32 v58, v226
	v_mov_b32_e32 v59, v227
	v_mul_f32_e32 v37, v37, v49
	s_waitcnt vmcnt(0)
	v_mul_f32_e32 v49, v56, v40
	v_mul_f32_e32 v49, v49, v47
	v_mul_f32_e32 v47, v52, v40
	v_mul_f32_e32 v47, v47, v48
	v_mul_f32_e32 v48, v57, v40
	v_mul_f32_e32 v48, v48, v45
	v_mul_f32_e32 v45, v53, v40
	v_mul_f32_e32 v45, v45, v46
	v_mul_f32_e32 v46, v58, v40
	v_mul_f32_e32 v46, v46, v43
	v_mul_f32_e32 v43, v54, v40
	v_mul_f32_e32 v43, v43, v44
	v_mul_f32_e32 v44, v59, v40
	v_mov_b32_e32 v58, v228
	v_mov_b32_e32 v59, v229
	v_mov_b32_e32 v60, v230
	v_mov_b32_e32 v61, v231
	v_mov_b32_e32 v62, v232
	v_mov_b32_e32 v63, v233
	v_mov_b32_e32 v64, v234
	v_mov_b32_e32 v65, v235
	v_mul_f32_e32 v44, v44, v41
	v_mul_f32_e32 v41, v55, v40
	v_mul_f32_e32 v41, v41, v42
	s_waitcnt vmcnt(0)
	v_mul_f32_e32 v42, v62, v40
	v_mul_f32_e32 v57, v42, v6
	v_mul_f32_e32 v6, v58, v40
	v_mul_f32_e32 v53, v6, v7
	v_mul_f32_e32 v6, v63, v40
	v_mul_f32_e32 v56, v6, v4
	v_mul_f32_e32 v4, v59, v40
	v_mul_f32_e32 v52, v4, v5
	v_mul_f32_e32 v4, v64, v40
	v_mul_f32_e32 v55, v4, v2
	v_mul_f32_e32 v2, v60, v40
	v_mul_f32_e32 v51, v2, v3
	v_mul_f32_e32 v2, v65, v40
	v_mul_f32_e32 v54, v2, v0
	v_mul_f32_e32 v0, v61, v40
	v_mul_f32_e32 v42, v0, v1
	v_mov_b32_e32 v0, v236
	v_mov_b32_e32 v1, v237
	v_mov_b32_e32 v2, v238
	v_mov_b32_e32 v3, v239
	v_mov_b32_e32 v4, v240
	v_mov_b32_e32 v5, v241
	v_mov_b32_e32 v6, v242
	v_mov_b32_e32 v7, v243
	s_waitcnt vmcnt(1)
	v_mul_f32_e32 v3, v3, v40
	v_mul_f32_e32 v3, v3, v8
	v_cvt_f32_i32_e32 v8, s4
	s_waitcnt vmcnt(0)
; DEV void attn_unit(int b, int h, int qb, const bf16_t* Q, const bf16_t* K, const bf16_t* V, bf16_t* O, LAS unsigned char* sh, const int tid, const float* qgain) {
;     ...
;         const int tq = qb * 256 + wid * 32 + r32; const float pr = (float)(tq >> 6), pc = (float)(tq & 63);
; #pragma unroll
;         for (int e = 0; e < 8; ++e) { const float invf = exp2f(-(float)e * (13.287712379549449f / 8.f));
;             const float rr_ = pr * invf * 0.15915494309189535f, rc_ = pc * invf * 0.15915494309189535f;
;             const float sr = __builtin_amdgcn_sinf(rr_), cr = __builtin_amdgcn_cosf(rr_), sc_ = __builtin_amdgcn_sinf(rc_), cc = __builtin_amdgcn_cosf(rc_);
;             const float o4 = qv[4][e], o5 = qv[5][e], p4 = __shfl_xor(o4, 32), p5 = __shfl_xor(o5, 32);
;             qv[4][e] = hi ? (p4 * sr + o4 * cr) : (o4 * cr - p4 * sr);
;             qv[5][e] = hi ? (p5 * sc_ + o5 * cc) : (o5 * cc - p5 * sc_); }
	v_mul_f32_e32 v4, v4, v40
	v_mul_f32_e32 v2, v2, v40
	v_mul_f32_e32 v7, v7, v40
	v_mul_f32_e32 v4, v4, v14
	v_mul_f32_e32 v5, v5, v40
	v_mul_f32_e32 v2, v2, v9
	v_mul_f32_e32 v7, v7, v10
	v_and_or_b32 v9, s14, 32, v132
	v_mul_f32_e32 v10, 0.15915494, v8
	ds_bpermute_b32 v14, v141, v57
	v_mul_f32_e32 v0, v0, v40
	v_mul_f32_e32 v5, v5, v12
	v_mul_f32_e32 v6, v6, v40
	v_cvt_f32_ubyte0_e32 v9, v9
	v_sin_f32_e32 v12, v10
	v_mul_f32_e32 v0, v0, v15
	v_mul_f32_e32 v1, v1, v40
	v_mul_f32_e32 v6, v6, v11
	v_mul_f32_e32 v11, 0.15915494, v9
	ds_bpermute_b32 v15, v141, v4
	v_mul_f32_e32 v1, v1, v13
	v_cos_f32_e32 v10, v10
	v_sin_f32_e32 v13, v11
	v_cos_f32_e32 v11, v11
	s_waitcnt lgkmcnt(1)
	v_mul_f32_e32 v12, v12, v14
	v_cndmask_b32_e64 v12, v12, -v12, s[2:3]
	v_fmac_f32_e32 v12, v10, v57
	s_waitcnt lgkmcnt(0)
	v_mul_f32_e32 v10, v13, v15
	v_cndmask_b32_e64 v10, v10, -v10, s[2:3]
	v_fmac_f32_e32 v10, v11, v4
	v_mul_f32_e32 v4, 0x3ea1e89b, v8
	v_mul_f32_e32 v4, 0.15915494, v4
	ds_bpermute_b32 v15, v141, v56
	v_mul_f32_e32 v11, 0x3ea1e89b, v9
	v_sin_f32_e32 v13, v4
	v_mul_f32_e32 v11, 0.15915494, v11
	ds_bpermute_b32 v40, v141, v5
	v_cos_f32_e32 v4, v4
	v_sin_f32_e32 v14, v11
	v_cos_f32_e32 v11, v11
	s_waitcnt lgkmcnt(1)
	v_mul_f32_e32 v13, v13, v15
	v_cndmask_b32_e64 v13, v13, -v13, s[2:3]
	v_fmac_f32_e32 v13, v4, v56
	s_waitcnt lgkmcnt(0)
	v_mul_f32_e32 v4, v14, v40
	v_cndmask_b32_e64 v4, v4, -v4, s[2:3]
	v_fmac_f32_e32 v4, v11, v5
	v_mul_f32_e32 v5, 0x3dcccccd, v8
	v_mul_f32_e32 v5, 0.15915494, v5
	ds_bpermute_b32 v40, v141, v55
	v_mul_f32_e32 v11, 0x3dcccccd, v9
	v_sin_f32_e32 v14, v5
	v_mul_f32_e32 v11, 0.15915494, v11
	ds_bpermute_b32 v50, v141, v6
	v_cos_f32_e32 v5, v5
	v_sin_f32_e32 v15, v11
	v_cos_f32_e32 v11, v11
	s_waitcnt lgkmcnt(1)
	v_mul_f32_e32 v14, v14, v40
	v_cndmask_b32_e64 v14, v14, -v14, s[2:3]
	v_fmac_f32_e32 v14, v5, v55
	s_waitcnt lgkmcnt(0)
	v_mul_f32_e32 v5, v15, v50
	v_cndmask_b32_e64 v5, v5, -v5, s[2:3]
	v_fmac_f32_e32 v5, v11, v6
	v_mul_f32_e32 v6, 0x3d0186e3, v8
	v_mul_f32_e32 v6, 0.15915494, v6
	ds_bpermute_b32 v50, v141, v54
	v_mul_f32_e32 v11, 0x3d0186e3, v9
	v_sin_f32_e32 v15, v6
	v_mul_f32_e32 v11, 0.15915494, v11
	ds_bpermute_b32 v55, v141, v7
	v_cos_f32_e32 v6, v6
	v_sin_f32_e32 v40, v11
	v_cos_f32_e32 v11, v11
	s_waitcnt lgkmcnt(1)
	v_mul_f32_e32 v15, v15, v50
	v_cndmask_b32_e64 v15, v15, -v15, s[2:3]
	v_fmac_f32_e32 v15, v6, v54
	s_waitcnt lgkmcnt(0)
	v_mul_f32_e32 v6, v40, v55
	v_cndmask_b32_e64 v6, v6, -v6, s[2:3]
	v_fmac_f32_e32 v6, v11, v7
	v_mul_f32_e32 v7, 0x3c23d70b, v8
	v_mul_f32_e32 v7, 0.15915494, v7
	ds_bpermute_b32 v54, v141, v53
	v_mul_f32_e32 v11, 0x3c23d70b, v9
	v_sin_f32_e32 v40, v7
	v_mul_f32_e32 v11, 0.15915494, v11
	ds_bpermute_b32 v55, v141, v0
	v_cos_f32_e32 v7, v7
	v_sin_f32_e32 v50, v11
	v_cos_f32_e32 v11, v11
	s_waitcnt lgkmcnt(1)
	v_mul_f32_e32 v40, v40, v54
	v_cndmask_b32_e64 v40, v40, -v40, s[2:3]
	v_fmac_f32_e32 v40, v7, v53
	s_waitcnt lgkmcnt(0)
	v_mul_f32_e32 v7, v50, v55
	v_cndmask_b32_e64 v7, v7, -v7, s[2:3]
	v_fmac_f32_e32 v7, v11, v0
	v_mul_f32_e32 v0, 0x3b4f3e39, v8
	v_mul_f32_e32 v0, 0.15915494, v0
	ds_bpermute_b32 v54, v141, v52
	v_mul_f32_e32 v11, 0x3b4f3e39, v9
	v_sin_f32_e32 v50, v0
	v_mul_f32_e32 v11, 0.15915494, v11
	ds_bpermute_b32 v55, v141, v1
	v_cos_f32_e32 v0, v0
	v_sin_f32_e32 v53, v11
	v_cos_f32_e32 v11, v11
	s_waitcnt lgkmcnt(1)
	v_mul_f32_e32 v50, v50, v54
	v_cndmask_b32_e64 v50, v50, -v50, s[2:3]
	v_fmac_f32_e32 v50, v0, v52
	s_waitcnt lgkmcnt(0)
	v_mul_f32_e32 v0, v53, v55
	v_cndmask_b32_e64 v0, v0, -v0, s[2:3]
	v_fmac_f32_e32 v0, v11, v1
	v_mul_f32_e32 v1, 0x3a831270, v8
	v_mul_f32_e32 v1, 0.15915494, v1
	ds_bpermute_b32 v54, v141, v51
	v_mul_f32_e32 v11, 0x3a831270, v9
	v_sin_f32_e32 v52, v1
	v_mul_f32_e32 v11, 0.15915494, v11
	ds_bpermute_b32 v55, v141, v2
	v_cos_f32_e32 v1, v1
	v_sin_f32_e32 v53, v11
	v_cos_f32_e32 v11, v11
	s_waitcnt lgkmcnt(1)
	v_mul_f32_e32 v52, v52, v54
	v_cndmask_b32_e64 v52, v52, -v52, s[2:3]
	v_fmac_f32_e32 v52, v1, v51
	s_waitcnt lgkmcnt(0)
	v_mul_f32_e32 v1, v53, v55
	v_cndmask_b32_e64 v1, v1, -v1, s[2:3]
	v_fmac_f32_e32 v1, v11, v2
	v_mul_f32_e32 v2, 0x39a5cb61, v8
	v_mul_f32_e32 v2, 0.15915494, v2
	ds_bpermute_b32 v51, v141, v42
	v_mul_f32_e32 v8, 0x39a5cb61, v9
	v_sin_f32_e32 v9, v2
	v_mul_f32_e32 v8, 0.15915494, v8
	ds_bpermute_b32 v53, v141, v3
	v_cos_f32_e32 v2, v2
	v_sin_f32_e32 v11, v8
	v_cos_f32_e32 v8, v8
	s_waitcnt lgkmcnt(1)
; DEV unsigned cvt_pk_bf16(float lo, float hi) { unsigned r; asm volatile("v_cvt_pk_bf16_f32 %0, %1, %2" : "=v"(r) : "v"(lo), "v"(hi)); return r; }
; DEV void attn_unit(int b, int h, int qb, const bf16_t* Q, const bf16_t* K, const bf16_t* V, bf16_t* O, LAS unsigned char* sh, const int tid, const float* qgain) {
;     ...
;         for (int d0 = 0; d0 < 6; ++d0) { u32x4 w; w.x = cvt_pk_bf16(qv[d0][0] * QSCALE, qv[d0][1] * QSCALE); w.y = cvt_pk_bf16(qv[d0][2] * QSCALE, qv[d0][3] * QSCALE);
;             w.z = cvt_pk_bf16(qv[d0][4] * QSCALE, qv[d0][5] * QSCALE); w.w = cvt_pk_bf16(qv[d0][6] * QSCALE, qv[d0][7] * QSCALE); qr[d0] = __builtin_bit_cast(bf16x8, w); }
;     ...
;     float mrun = 0.f, lsum = 0.f; f32x16 o[2]; o[0] = f32x16{}; o[1] = f32x16{}; const f32x16 zero16 = f32x16{};
	v_mul_f32_e32 v9, v9, v51
	v_cndmask_b32_e64 v9, v9, -v9, s[2:3]
	v_fmac_f32_e32 v9, v2, v42
	s_waitcnt lgkmcnt(0)
	v_mul_f32_e32 v2, v11, v53
	v_cndmask_b32_e64 v2, v2, -v2, s[2:3]
	v_fmac_f32_e32 v2, v8, v3
	v_mul_f32_e32 v3, 0x3e16c740, v18
	v_mul_f32_e32 v8, 0x3e16c740, v20
	v_cvt_pk_bf16_f32 v110, v3, v8
	v_mul_f32_e32 v3, 0x3e16c740, v22
	v_mul_f32_e32 v8, 0x3e16c740, v23
	v_cvt_pk_bf16_f32 v111, v3, v8
	v_mul_f32_e32 v3, 0x3e16c740, v16
	v_mul_f32_e32 v8, 0x3e16c740, v17
	v_cvt_pk_bf16_f32 v112, v3, v8
	v_mul_f32_e32 v3, 0x3e16c740, v19
	v_mul_f32_e32 v8, 0x3e16c740, v21
	v_cvt_pk_bf16_f32 v113, v3, v8
	v_mul_f32_e32 v3, 0x3e16c740, v26
	v_mul_f32_e32 v8, 0x3e16c740, v28
	v_cvt_pk_bf16_f32 v106, v3, v8
	v_mul_f32_e32 v3, 0x3e16c740, v30
	v_mul_f32_e32 v8, 0x3e16c740, v31
	v_cvt_pk_bf16_f32 v107, v3, v8
	v_mul_f32_e32 v3, 0x3e16c740, v24
	v_mul_f32_e32 v8, 0x3e16c740, v25
	v_cvt_pk_bf16_f32 v108, v3, v8
	v_mul_f32_e32 v3, 0x3e16c740, v27
	v_mul_f32_e32 v8, 0x3e16c740, v29
	v_cvt_pk_bf16_f32 v109, v3, v8
	v_mul_f32_e32 v3, 0x3e16c740, v34
	v_mul_f32_e32 v8, 0x3e16c740, v36
	v_cvt_pk_bf16_f32 v114, v3, v8
	v_mul_f32_e32 v3, 0x3e16c740, v38
	v_mul_f32_e32 v8, 0x3e16c740, v39
	v_cvt_pk_bf16_f32 v115, v3, v8
	v_mul_f32_e32 v3, 0x3e16c740, v32
	v_mul_f32_e32 v8, 0x3e16c740, v33
	v_cvt_pk_bf16_f32 v116, v3, v8
	v_mul_f32_e32 v3, 0x3e16c740, v35
	v_mul_f32_e32 v8, 0x3e16c740, v37
	v_cvt_pk_bf16_f32 v117, v3, v8
	v_mul_f32_e32 v3, 0x3e16c740, v49
	v_mul_f32_e32 v8, 0x3e16c740, v48
	v_cvt_pk_bf16_f32 v118, v3, v8
	v_mul_f32_e32 v3, 0x3e16c740, v46
	v_mul_f32_e32 v8, 0x3e16c740, v44
	v_cvt_pk_bf16_f32 v119, v3, v8
	v_mul_f32_e32 v3, 0x3e16c740, v47
	v_mul_f32_e32 v8, 0x3e16c740, v45
	v_cvt_pk_bf16_f32 v120, v3, v8
	v_mul_f32_e32 v3, 0x3e16c740, v43
	v_mul_f32_e32 v8, 0x3e16c740, v41
	v_cvt_pk_bf16_f32 v121, v3, v8
	v_mul_f32_e32 v3, 0x3e16c740, v12
	v_mul_f32_e32 v8, 0x3e16c740, v13
	v_cvt_pk_bf16_f32 v102, v3, v8
	v_mul_f32_e32 v3, 0x3e16c740, v14
	v_mul_f32_e32 v8, 0x3e16c740, v15
	v_cvt_pk_bf16_f32 v103, v3, v8
	v_mul_f32_e32 v3, 0x3e16c740, v40
	v_mul_f32_e32 v8, 0x3e16c740, v50
	v_cvt_pk_bf16_f32 v104, v3, v8
	v_mul_f32_e32 v3, 0x3e16c740, v52
	v_mul_f32_e32 v8, 0x3e16c740, v9
	v_cvt_pk_bf16_f32 v105, v3, v8
	v_mul_f32_e32 v3, 0x3e16c740, v10
	v_mul_f32_e32 v4, 0x3e16c740, v4
	v_cvt_pk_bf16_f32 v98, v3, v4
	v_mul_f32_e32 v3, 0x3e16c740, v5
	v_mul_f32_e32 v0, 0x3e16c740, v0
	v_readlane_b32 s4, v251, 44
	v_mul_f32_e32 v4, 0x3e16c740, v6
	v_cvt_pk_bf16_f32 v99, v3, v4
	v_mul_f32_e32 v3, 0x3e16c740, v7
	v_cvt_pk_bf16_f32 v100, v3, v0
	v_mul_f32_e32 v0, 0x3e16c740, v1
	v_mul_f32_e32 v1, 0x3e16c740, v2
	v_readlane_b32 s5, v251, 45
	v_cvt_pk_bf16_f32 v101, v0, v1
	s_lshl_b32 s33, s21, 8
	s_lshl_b32 s22, s21, 10
	s_cmp_lt_u32 s21, 4
	s_cselect_b32 s23, 1, 0
	v_lshl_add_u32 v143, v132, 2, s33
	s_lshl_b32 s27, s20, 7
	s_mul_i32 s4, s8, 0xc00
	s_mul_i32 s5, s20, 0xc0
	s_lshl_b32 s25, s21, 4
	s_add_u32 s5, s5, s25
	s_add_u32 s4, s4, s5
	s_lshr_b32 s25, s8, 4
	s_add_u32 s25, s25, 0x8000
	s_mul_i32 s26, s25, 0xc00
	s_add_u32 s26, s26, s5
	v_readlane_b32 s12, v251, 44
	v_readlane_b32 s13, v251, 45
	v_mul_u32_u24_e32 v128, 0xc00, v130
	v_lshlrev_b32_e32 v145, 11, v136
	s_add_u32 s36, s12, s26
	s_addc_u32 s37, s13, 0
	s_add_u32 s12, s12, s4
	s_addc_u32 s13, s13, 0
	s_and_b32 s5, s21, 3
	s_lshl_b32 s5, s5, 4
	s_add_u32 s4, s8, s5
	s_lshl_b32 s4, s4, 11
	s_lshr_b32 s34, s21, 2
	s_lshl_b32 s34, s34, 6
	s_add_u32 s34, s34, s27
	s_add_u32 s4, s4, s34
	s_add_u32 s25, s25, s5
	s_lshl_b32 s25, s25, 11
	s_add_u32 s25, s25, s34
	v_readlane_b32 s14, v251, 35
	v_readlane_b32 s15, v251, 36
	v_add_u32_e32 v129, 0x80, v128
	v_lshl_add_u32 v145, v138, 1, v145
	s_add_u32 s38, s14, s25
	s_addc_u32 s39, s15, 0
	s_add_u32 s14, s14, s4
	s_addc_u32 s15, s15, 0
	v_add_u32_e32 v126, 0x10000, v194
	v_add_u32_e32 v127, 0x10000, v139
	s_add_i32 m0, s22, 0x0
	s_cmp_eq_u32 s23, 0
	global_load_lds_dwordx4 v128, s[12:13]
	s_cbranch_scc1 .Lat_k2_1
	s_add_i32 m0, s22, 0x2000
	s_nop 0
	global_load_lds_dwordx4 v129, s[12:13]
